# barrier: XCD members poll the global release flag directly (skip leader relay hop)
# speedup vs baseline: 1.0051x; 1.0051x over previous
; __device__ __forceinline__ unsigned xb_ld(unsigned* p)              { return __hip_atomic_load(p, __ATOMIC_RELAXED, __HIP_MEMORY_SCOPE_AGENT); }
; __device__ __forceinline__ unsigned xb_add(unsigned* p, unsigned v) { return __hip_atomic_fetch_add(p, v, __ATOMIC_RELAXED, __HIP_MEMORY_SCOPE_AGENT); }
; #define XB_SPIN(cond, bar) do { unsigned _sp = 0; while (cond) { __builtin_amdgcn_s_sleep(1); \
;     if ((++_sp & 255u) == 0u) { if (xb_ld(&(bar)[XB_TMO])) break; if (_sp > XB_SPIN_CAP) { atomicAdd(&(bar)[XB_TMO], 1u); break; } } } } while (0)
; __device__ __forceinline__ void xcd_barrier(const XcdBarrier& b) {
;     ...
;         const unsigned old = xb_add(&bar[XB_XSUB(b.x)], 1u);
;         const unsigned gen = old / nloc;
;         if (old + 1u == (gen + 1u) * nloc) {
;             __builtin_amdgcn_fence(__ATOMIC_RELEASE, "agent");
;             asm volatile("s_waitcnt vmcnt(0)" ::: "memory");
;             const unsigned og = xb_add(&bar[XB_TOP], 1u);
;             const unsigned tg = og / nx;
;             if (og + 1u == (tg + 1u) * nx) xb_add(&bar[XB_TOPGEN], 1u);
;             else XB_SPIN(xb_ld(&bar[XB_TOPGEN]) == tg, bar);
;             __builtin_amdgcn_fence(__ATOMIC_ACQUIRE, "agent");
;             xb_add(&bar[XB_XGEN(b.x)], 1u);
;             asm volatile("s_waitcnt vmcnt(0)" ::: "memory");
;         } else {
;             XB_SPIN(xb_ld(&bar[XB_XGEN(b.x)]) == gen, bar);
.LBB0_1974:
	s_lshl_b32 s24, s33, 6
	s_add_i32 s56, s24, 0x500
	s_lshl_b64 s[4:5], s[56:57], 2
	s_add_u32 s4, s2, s4
	s_addc_u32 s5, s3, s5
	v_mov_b64_e32 v[4:5], s[4:5]
	v_mov_b32_e32 v1, 1
	flat_atomic_add v3, v[4:5], v1 sc0
	v_cvt_f32_u32_e32 v1, v2
	v_sub_u32_e32 v4, 0, v2
	v_rcp_iflag_f32_e32 v1, v1
	s_nop 0
	v_mul_f32_e32 v1, 0x4f7ffffe, v1
	v_cvt_u32_f32_e32 v1, v1
	v_mul_lo_u32 v4, v4, v1
	v_mul_hi_u32 v4, v1, v4
	v_add_u32_e32 v1, v1, v4
	s_waitcnt vmcnt(0) lgkmcnt(0)
	v_mul_hi_u32 v1, v3, v1
	v_mul_lo_u32 v4, v1, v2
	v_sub_u32_e32 v4, v3, v4
	v_cmp_ge_u32_e32 vcc, v4, v2
	v_add_u32_e32 v5, 1, v1
	s_nop 0
	v_cndmask_b32_e32 v1, v1, v5, vcc
	v_sub_u32_e32 v5, v4, v2
	v_cndmask_b32_e32 v4, v4, v5, vcc
	v_cmp_ge_u32_e32 vcc, v4, v2
	v_add_u32_e32 v4, 1, v1
	s_nop 0
	v_cndmask_b32_e32 v1, v1, v4, vcc
	v_add_u32_e32 v4, 1, v3
	v_mad_u64_u32 v[2:3], s[4:5], v2, v1, v[2:3]
	v_cmp_ne_u32_e32 vcc, v4, v2
	s_and_saveexec_b64 s[4:5], vcc
	s_xor_b64 s[4:5], exec, s[4:5]
	s_cbranch_execz .LBB0_1987
	s_add_u32 s8, s2, 0x3500
	s_addc_u32 s9, s3, 0
	v_mov_b64_e32 v[2:3], s[8:9]
	flat_load_dword v0, v[2:3] sc1
	s_waitcnt vmcnt(0) lgkmcnt(0)
	v_cmp_eq_u32_e32 vcc, v0, v1
	s_and_saveexec_b64 s[6:7], vcc
	s_cbranch_execz .LBB0_1986
	s_mov_b32 s25, 1
	s_mov_b64 s[10:11], 0
	s_branch .LBB0_1978
